# adds batched rwprep loads (row loads, v_first loads, LoRA operand loads), GL/HG item prefetch de-serialization
# baseline (speedup 1.0000x reference)
; __device__ __forceinline__ void phase_rwprep(const Params& p, int l, LAS unsigned char* lds, int tid, int lane, int wave) {
;     ...
;             for (int ci = 0; ci < 3; ++ci) {
;                 const int ct = wave + 8 * ci, col = 16 * ct + row;
;                 f32x4 aw = {0.f, 0.f, 0.f, 0.f}, aa = aw, ag = aw, av = aw;
; #pragma unroll
;                 for (int kc = 0; kc < 2; ++kc) {
;                     aw = __builtin_amdgcn_mfma_f32_16x16x32_bf16(af[kc], *(const pg8::bf16x8*)(LW + (size_t)col * 64 + 32 * kc + 8 * q), aw, 0, 0, 0);
;                     aa = __builtin_amdgcn_mfma_f32_16x16x32_bf16(af[2 + kc], *(const pg8::bf16x8*)(LA + (size_t)col * 64 + 32 * kc + 8 * q), aa, 0, 0, 0);
;                 }
; #pragma unroll
;                 for (int kc = 0; kc < 4; ++kc)
;                     ag = __builtin_amdgcn_mfma_f32_16x16x32_bf16(af[4 + kc], *(const pg8::bf16x8*)(LG + (size_t)col * 128 + 32 * kc + 8 * q), ag, 0, 0, 0);
;                 if (l > 0) av = __builtin_amdgcn_mfma_f32_16x16x32_bf16(af[8], *(const pg8::bf16x8*)(LV + (size_t)col * 32 + 8 * q), av, 0, 0, 0);
; #pragma unroll
;                 for (int i = 0; i < 4; ++i) {
;                     const int o = (4 * q + i) * RWW + col;
;                     outL[0 * 16 * RWW + o] = aw[i]; outL[1 * 16 * RWW + o] = aa[i]; outL[2 * 16 * RWW + o] = ag[i]; outL[3 * 16 * RWW + o] = av[i];
;                 }
;             }
.LBB0_889:
	s_or_b64 exec, exec, s[10:11]
	v_bfe_u32 v2, v3, 16, 1
	v_add3_u32 v2, v3, v2, s61
	ds_write_b16_d16_hi v150, v2
	s_waitcnt lgkmcnt(0)
	s_barrier
	global_load_dwordx4 v[2:5], v[108:109], off
	global_load_dwordx4 v[6:9], v[104:105], off
	global_load_dwordx4 v[30:33], v[106:107], off
	global_load_dwordx4 v[34:37], v[108:109], off offset:64
	ds_read_b128 v[26:29], v224 offset:256
	ds_read_b128 v[18:21], v224
	ds_read_b128 v[14:17], v224 offset:128
	ds_read_b128 v[22:25], v224 offset:320
	global_load_dwordx4 v[38:41], v[104:105], off offset:64
	global_load_dwordx4 v[46:49], v[106:107], off offset:64
	global_load_dwordx4 v[226:229], v[108:109], off offset:128
	global_load_dwordx4 v[230:233], v[108:109], off offset:192
	global_load_dwordx4 v[234:237], v[110:111], off
	ds_read_b128 v[10:13], v224 offset:64
	s_andn2_b64 vcc, exec, s[56:57]
	v_mov_b32_e32 v54, 0
	v_mov_b32_e32 v55, 0
	s_waitcnt vmcnt(8) lgkmcnt(4)
	v_mfma_f32_16x16x32_bf16 v[2:5], v[26:29], v[2:5], 0
	s_waitcnt vmcnt(7) lgkmcnt(3)
	v_mfma_f32_16x16x32_bf16 v[42:45], v[18:21], v[6:9], 0
	ds_read_b128 v[6:9], v224 offset:192
	s_waitcnt vmcnt(6) lgkmcnt(3)
	v_mfma_f32_16x16x32_bf16 v[50:53], v[14:17], v[30:33], 0
	ds_read_b128 v[30:33], v224 offset:384
	s_waitcnt vmcnt(5) lgkmcnt(3)
	v_mfma_f32_16x16x32_bf16 v[2:5], v[22:25], v[34:37], v[2:5]
	ds_read_b128 v[34:37], v224 offset:448
	s_waitcnt vmcnt(4) lgkmcnt(3)
	v_mfma_f32_16x16x32_bf16 v[40:43], v[10:13], v[38:41], v[42:45]
	v_cndmask_b32_e64 v39, 0, 1, s[56:57]
	v_mov_b32_e32 v38, 0
	v_cmp_ne_u32_e64 s[64:65], 1, v39
	s_waitcnt vmcnt(3) lgkmcnt(2)
	v_mfma_f32_16x16x32_bf16 v[44:47], v[6:9], v[46:49], v[50:53]
	s_waitcnt vmcnt(2) lgkmcnt(1)
	v_mfma_f32_16x16x32_bf16 v[48:51], v[30:33], v[226:229], v[2:5]
	s_nop 0
	v_mov_b32_e32 v52, 0
	v_mov_b32_e32 v53, 0
	ds_read_b128 v[2:5], v224 offset:512
	s_waitcnt vmcnt(1) lgkmcnt(1)
	v_mfma_f32_16x16x32_bf16 v[48:51], v[34:37], v[230:233], v[48:51]
	s_cbranch_vccnz .LBB0_891
	s_waitcnt vmcnt(0) lgkmcnt(0)
	v_mfma_f32_16x16x32_bf16 v[52:55], v[2:5], v[234:237], 0
.LBB0_891:
	s_nop 3
	ds_write_b32 v152, v48 offset:49152
	s_nop 2
	ds_write_b32 v153, v52
	ds_write2st64_b32 v151, v40, v41 offset0:64 offset1:70
	ds_write2st64_b32 v151, v44, v45 offset0:160 offset1:166
	ds_write_b32 v154, v49 offset:49152
	ds_write_b32 v155, v53
	ds_write_b32 v156, v50 offset:49152
	ds_write_b32 v157, v54
	ds_write2st64_b32 v151, v42, v43 offset0:76 offset1:82
	ds_write2st64_b32 v151, v46, v47 offset0:172 offset1:178
	ds_write_b32 v158, v51 offset:49152
	ds_write_b32 v159, v55
	global_load_dwordx4 v[46:49], v[112:113], off
	global_load_dwordx4 v[50:53], v[114:115], off
	global_load_dwordx4 v[226:229], v[112:113], off offset:64
	global_load_dwordx4 v[230:233], v[114:115], off offset:64
	global_load_dwordx4 v[40:43], v[116:117], off
	global_load_dwordx4 v[234:237], v[116:117], off offset:64
	global_load_dwordx4 v[238:241], v[116:117], off offset:128
	global_load_dwordx4 v[242:245], v[116:117], off offset:192
	global_load_dwordx4 v[246:249], v[118:119], off
	s_and_b64 vcc, exec, s[64:65]
	v_mov_b32_e32 v39, 0
	s_waitcnt vmcnt(8)
	v_mfma_f32_16x16x32_bf16 v[46:49], v[18:21], v[46:49], 0
	s_waitcnt vmcnt(4)
	v_mfma_f32_16x16x32_bf16 v[40:43], v[26:29], v[40:43], 0
	s_waitcnt vmcnt(3)
	v_mfma_f32_16x16x32_bf16 v[40:43], v[22:25], v[234:237], v[40:43]
	v_mfma_f32_16x16x32_bf16 v[50:53], v[14:17], v[50:53], 0
	v_mfma_f32_16x16x32_bf16 v[46:49], v[10:13], v[226:229], v[46:49]
	v_mfma_f32_16x16x32_bf16 v[50:53], v[6:9], v[230:233], v[50:53]
	s_waitcnt vmcnt(2)
	v_mfma_f32_16x16x32_bf16 v[40:43], v[30:33], v[238:241], v[40:43]
	s_waitcnt vmcnt(1)
	v_mfma_f32_16x16x32_bf16 v[42:45], v[34:37], v[242:245], v[40:43]
	s_nop 4
	v_mov_b32_e32 v40, 0
	v_mov_b32_e32 v41, 0
	s_cbranch_vccnz .LBB0_893
	s_waitcnt vmcnt(0) lgkmcnt(12)
	v_mfma_f32_16x16x32_bf16 v[38:41], v[2:5], v[246:249], 0
.LBB0_893:
	ds_write_b32 v175, v42 offset:49152
	s_nop 6
	ds_write_b32 v176, v38
	ds_write2st64_b32 v151, v46, v47 offset0:66 offset1:72
	ds_write2st64_b32 v151, v50, v51 offset0:162 offset1:168
	ds_write_b32 v177, v43 offset:49152
	ds_write_b32 v178, v39
	ds_write_b32 v179, v44 offset:49152
	ds_write_b32 v180, v40
	ds_write2st64_b32 v151, v48, v49 offset0:78 offset1:84
	ds_write2st64_b32 v151, v52, v53 offset0:174 offset1:180
	ds_write_b32 v181, v45 offset:49152
	ds_write_b32 v182, v41
	global_load_dwordx4 v[38:41], v[120:121], off
	global_load_dwordx4 v[42:45], v[122:123], off
	global_load_dwordx4 v[46:49], v[120:121], off offset:64
	global_load_dwordx4 v[50:53], v[122:123], off offset:64
	global_load_dwordx4 v[226:229], v[124:125], off
	global_load_dwordx4 v[238:241], v[124:125], off offset:64
	global_load_dwordx4 v[242:245], v[124:125], off offset:128
	global_load_dwordx4 v[246:249], v[124:125], off offset:192
	global_load_dwordx4 v[234:237], v[126:127], off
	s_and_b64 vcc, exec, s[64:65]
	s_waitcnt vmcnt(8)
	v_mfma_f32_16x16x32_bf16 v[18:21], v[18:21], v[38:41], 0
	s_waitcnt vmcnt(4)
	v_mfma_f32_16x16x32_bf16 v[26:29], v[26:29], v[226:229], 0
	v_mfma_f32_16x16x32_bf16 v[14:17], v[14:17], v[42:45], 0
	v_mfma_f32_16x16x32_bf16 v[10:13], v[10:13], v[46:49], v[18:21]
	v_mfma_f32_16x16x32_bf16 v[6:9], v[6:9], v[50:53], v[14:17]
	s_nop 5
	v_mov_b32_e32 v14, 0
	v_mov_b32_e32 v15, 0
	v_mov_b32_e32 v16, 0
	v_mov_b32_e32 v17, 0
	s_waitcnt vmcnt(3)
	v_mfma_f32_16x16x32_bf16 v[22:25], v[22:25], v[238:241], v[26:29]
	s_waitcnt vmcnt(2)
	v_mfma_f32_16x16x32_bf16 v[22:25], v[30:33], v[242:245], v[22:25]
	s_waitcnt vmcnt(1)
	v_mfma_f32_16x16x32_bf16 v[22:25], v[34:37], v[246:249], v[22:25]
	s_cbranch_vccnz .LBB0_895
	s_waitcnt vmcnt(0) lgkmcnt(14)
	v_mfma_f32_16x16x32_bf16 v[14:17], v[2:5], v[234:237], 0
